# walks: next-step load addresses precomputed at step top (mLSTM and GLA) so the loads issue back-to-back
# baseline (speedup 1.0000x reference)
.LBB0_445:
	v_cmp_lt_i32_e32 vcc, v84, v56
	s_cbranch_vccz .Lgla_pre_done
	v_add_u32_e32 v83, 1, v84
	v_cmp_gt_i32_e32 vcc, 3, v84
	s_nop 1
	v_cndmask_b32_e64 v85, v217, 3, vcc
	v_add3_u32 v85, v85, v0, -1
	v_cndmask_b32_e64 v85, v85, v83, s[60:61]
	v_add_u32_e32 v98, v85, v55
	v_mul_hi_i32 v85, v98, s7
	v_lshrrev_b32_e32 v99, 31, v85
	v_ashrrev_i32_e32 v85, 5, v85
	v_add_u32_e32 v85, v85, v99
	v_mul_lo_u32 v99, v85, s17
	v_sub_u32_e32 v99, v98, v99
	v_cmp_lt_i32_e32 vcc, 3, v99
	v_lshlrev_b32_e32 v99, 6, v99
	v_lshlrev_b32_e32 v100, 13, v85
	v_lshlrev_b32_e32 v101, 8, v85
	s_movk_i32 s19, 0xff00
	v_add3_u32 v100, v99, v100, s19
	s_mov_b32 s19, 0x8000
	v_add3_u32 v101, v101, v99, s19
	v_cndmask_b32_e32 v85, v101, v100, vcc
	s_movk_i32 s19, 0x300
	v_mad_i64_i32 v[100:101], s[30:31], v85, s19, 0
	v_lshl_add_u64 v[86:87], v[40:41], 0, v[100:101]
	v_lshl_add_u64 v[88:89], v[42:43], 0, v[100:101]
	v_lshl_add_u64 v[90:91], v[44:45], 0, v[100:101]
	v_add_u32_e32 v99, v85, v52
	v_mad_i64_i32 v[92:93], s[30:31], v99, s74, v[46:47]
	v_lshl_add_u32 v98, v98, 1, v39
	v_ashrrev_i32_e32 v99, 31, v98
	v_lshlrev_b64 v[98:99], 2, v[98:99]
	v_or_b32_e32 v98, v98, v38
	s_movk_i32 s19, 0xc0
	v_mad_u64_u32 v[94:95], s[30:31], v98, s19, v[72:73]
	v_mad_i32_i24 v95, v99, s19, v95
	v_add_u32_e32 v99, v85, v54
	v_mad_i64_i32 v[96:97], s[30:31], v99, s16, v[2:3]

.LBB0_455:
	s_or_b64 exec, exec, s[18:19]
	ds_write_b128 v139, v[20:23] offset:9216
	ds_write_b128 v182, v[24:27] offset:18432
	s_and_saveexec_b64 s[14:15], s[48:49]
	ds_write_b32 v131, v53 offset:32768
	s_or_b64 exec, exec, s[14:15]
	v_add_u32_e32 v83, 1, v84
	v_cmp_lt_i32_e32 vcc, v84, v56
	v_cmp_ge_i32_e64 s[64:65], v84, v56
	v_mov_b64_e32 v[48:49], v[28:29]
	v_mov_b64_e32 v[50:51], v[30:31]
	s_and_saveexec_b64 s[14:15], vcc
	s_cbranch_execz .LBB0_470
	s_and_b64 vcc, exec, s[62:63]
	s_mov_b64 s[18:19], s[26:27]
	s_cbranch_vccnz .LBB0_464
	global_load_dwordx4 v[12:15], v[86:87], off
	s_or_b64 s[18:19], s[26:27], exec
.LBB0_464:
	s_and_saveexec_b64 s[30:31], s[18:19]
	s_cbranch_execz .LBB0_466
	global_load_dwordx4 v[16:19], v[88:89], off
.LBB0_466:
	s_or_b64 exec, exec, s[30:31]
	global_load_dwordx4 v[20:23], v[90:91], off
	s_nop 0
	global_load_dwordx4 v[24:27], v[92:93], off offset:1280
	s_and_saveexec_b64 s[18:19], s[48:49]
	s_cbranch_execz .LBB0_468
	global_load_dword v53, v[94:95], off
.LBB0_468:
	s_or_b64 exec, exec, s[18:19]
	s_and_b64 vcc, exec, s[62:63]
	v_mov_b64_e32 v[48:49], v[28:29]
	v_mov_b64_e32 v[50:51], v[30:31]
	s_cbranch_vccnz .LBB0_470
	global_load_dwordx2 v[50:51], v[96:97], off
	global_load_dwordx2 v[48:49], v[96:97], off offset:32
